# attention: cross-lane max exchange only on the refresh path
# baseline (speedup 1.0000x reference)
; __device__ __forceinline__ void attn_phase(LAS unsigned char* ldsb, bf16_t* P, const bf16_t* Kn, const bf16_t* KPE, const bf16_t* VT) {
;     ...
;                     float mx = st[0][0];
; #pragma unroll
;                     for (int kb = 0; kb < 2; ++kb)
; #pragma unroll
;                         for (int i = 0; i < 16; ++i) mx = fmaxf(mx, st[kb][i]);
;                     mx = fmaxf(mx, __shfl_xor(mx, 32));
;                     if (__builtin_amdgcn_ballot_w64(mx > mrun) != 0ull) {
;                         const float mnew = fmaxf(mrun, mx);
;                         const float alpha = __builtin_amdgcn_exp2f(mrun - mnew);
;                         mrun = mnew; lrun *= alpha;
; #pragma unroll
;                         for (int d = 0; d < 4; ++d)
; #pragma unroll
;                             for (int i = 0; i < 16; ++i) o[d][i] *= alpha;
;                     }
.LBB0_1530:
	s_nop 9
	v_max_f32_e32 v0, v97, v97
	v_max_f32_e32 v2, v96, v96
	v_max_f32_e32 v0, v2, v0
	v_max3_f32 v0, v0, v98, v99
	v_max3_f32 v0, v0, v100, v101
	v_max3_f32 v0, v0, v102, v103
	v_max3_f32 v0, v0, v104, v105
	v_max3_f32 v0, v0, v106, v107
	v_max3_f32 v0, v0, v108, v109
	v_max3_f32 v0, v0, v110, v111
	v_max3_f32 v0, v0, v80, v81
	v_max3_f32 v0, v0, v82, v83
	v_max3_f32 v0, v0, v84, v85
	v_max3_f32 v0, v0, v86, v87
	v_max3_f32 v0, v0, v88, v89
	v_max3_f32 v0, v0, v90, v91
	v_max3_f32 v0, v0, v92, v93
	v_max3_f32 v0, v0, v94, v95
	v_sub_f32_e32 v2, v0, v240
	v_cmp_lt_f32_e32 vcc, 4.0, v2
	s_cbranch_vccz .LBB0_1525
	v_and_b32_e32 v3, 64, v234
	v_xor_b32_e32 v2, 32, v234
	v_add_u32_e32 v3, 64, v3
	v_cmp_lt_i32_e32 vcc, v2, v3
	s_nop 1
	v_cndmask_b32_e32 v2, v234, v2, vcc
	v_lshlrev_b32_e32 v2, 2, v2
	ds_bpermute_b32 v2, v2, v0
	s_waitcnt lgkmcnt(0)
	v_max_f32_e32 v2, v2, v2
	v_max_f32_e32 v0, v0, v2
	v_max_f32_e32 v0, v0, v0
	v_max_f32_e32 v2, v240, v240
	v_max_f32_e32 v2, v2, v0
	v_sub_f32_e32 v0, v240, v2
	v_exp_f32_e32 v0, v0
	v_mov_b32_e32 v240, v2
	v_pk_mul_f32 v[78:79], v[78:79], v[0:1] op_sel_hi:[1,0]
	v_pk_mul_f32 v[76:77], v[76:77], v[0:1] op_sel_hi:[1,0]
	v_pk_mul_f32 v[74:75], v[74:75], v[0:1] op_sel_hi:[1,0]
	v_pk_mul_f32 v[72:73], v[72:73], v[0:1] op_sel_hi:[1,0]
	v_pk_mul_f32 v[70:71], v[70:71], v[0:1] op_sel_hi:[1,0]
	v_pk_mul_f32 v[68:69], v[68:69], v[0:1] op_sel_hi:[1,0]
	v_pk_mul_f32 v[66:67], v[66:67], v[0:1] op_sel_hi:[1,0]
	v_pk_mul_f32 v[64:65], v[64:65], v[0:1] op_sel_hi:[1,0]
	v_pk_mul_f32 v[62:63], v[62:63], v[0:1] op_sel_hi:[1,0]
	v_pk_mul_f32 v[60:61], v[60:61], v[0:1] op_sel_hi:[1,0]
	v_pk_mul_f32 v[58:59], v[58:59], v[0:1] op_sel_hi:[1,0]
	v_pk_mul_f32 v[56:57], v[56:57], v[0:1] op_sel_hi:[1,0]
	v_pk_mul_f32 v[54:55], v[54:55], v[0:1] op_sel_hi:[1,0]
	v_pk_mul_f32 v[52:53], v[52:53], v[0:1] op_sel_hi:[1,0]
	v_pk_mul_f32 v[50:51], v[50:51], v[0:1] op_sel_hi:[1,0]
	v_pk_mul_f32 v[48:49], v[48:49], v[0:1] op_sel_hi:[1,0]
	v_pk_mul_f32 v[46:47], v[46:47], v[0:1] op_sel_hi:[1,0]
	v_pk_mul_f32 v[44:45], v[44:45], v[0:1] op_sel_hi:[1,0]
	v_pk_mul_f32 v[42:43], v[42:43], v[0:1] op_sel_hi:[1,0]
	v_pk_mul_f32 v[40:41], v[40:41], v[0:1] op_sel_hi:[1,0]
	v_pk_mul_f32 v[38:39], v[38:39], v[0:1] op_sel_hi:[1,0]
	v_pk_mul_f32 v[36:37], v[36:37], v[0:1] op_sel_hi:[1,0]
	v_pk_mul_f32 v[34:35], v[34:35], v[0:1] op_sel_hi:[1,0]
	v_pk_mul_f32 v[32:33], v[32:33], v[0:1] op_sel_hi:[1,0]
	v_pk_mul_f32 v[30:31], v[30:31], v[0:1] op_sel_hi:[1,0]
	v_pk_mul_f32 v[28:29], v[28:29], v[0:1] op_sel_hi:[1,0]
	v_pk_mul_f32 v[26:27], v[26:27], v[0:1] op_sel_hi:[1,0]
	v_pk_mul_f32 v[24:25], v[24:25], v[0:1] op_sel_hi:[1,0]
	v_pk_mul_f32 v[22:23], v[22:23], v[0:1] op_sel_hi:[1,0]
	v_pk_mul_f32 v[20:21], v[20:21], v[0:1] op_sel_hi:[1,0]
	v_pk_mul_f32 v[18:19], v[18:19], v[0:1] op_sel_hi:[1,0]
	v_pk_mul_f32 v[16:17], v[16:17], v[0:1] op_sel_hi:[1,0]
	v_mul_f32_e32 v236, v236, v0
	s_branch .LBB0_1525
